# last layer LN skips the unused XB bf16 copy; out main pass visits M-tile bands in descending order so the following LN reads the most recently written rows first
# speedup vs baseline: 1.1100x; 1.0059x over previous
; DI int otid() { int t = threadIdx.x; asm volatile("" : "+v"(t)); return t; }
;     DI bool next(int i, Unit& u) const {
;         const long L = (long)i * G + c; if (L >= nwg) return false;
;         int wgid = (int)L; { const int q = nwg / NXCD, r = nwg % NXCD, xcd = wgid % NXCD, off = wgid / NXCD; wgid = (xcd < r ? xcd * (q + 1) : r * (q + 1) + (xcd - r) * q) + off; }
;         const int nig = WGM * nN, gid = wgid / nig, fm = gid * WGM, gsz = (nM - fm) < WGM ? (nM - fm) : WGM;
;         u.pm = fm + ((wgid % nig) % gsz); u.pn = (wgid % nig) / gsz; return true;
;     }
; template <class Epi, class Sched>
; __device__ __forceinline__ void gemm_phase(PG8_LAS unsigned char* lds, const Gemm g, const Sched& S, const Epi& E) {
;     const int tid = otid(), wid = __builtin_amdgcn_readfirstlane(tid >> 6), lane = tid & 63, wr = wid >> 2, wc = wid & 3, fr = lane & 15, fq = lane >> 4;
;     const int K = g.K, nt = K / BK;
;     unsigned voffA[2], voffB[2];
; #pragma unroll
;     for (int i = 0; i < 2; ++i) { int R, C; stage_rc(tid * 16 + i * 8192, R, C); const int Rb = Epi::PERM ? ((R & ~31) + perm32(R & 31)) : R;
;         voffA[i] = (unsigned)(R * K + C) * 2u; voffB[i] = (unsigned)(Rb * K + C) * 2u; }
;     const size_t kstep = (size_t)(BK * 2);
;     const size_t hstep = (size_t)HALF * K * 2;
;     const size_t tstep = 2 * hstep;
;     const unsigned ldsw = (unsigned)wid * 1024u;
;     const int aoff = lds_byte(wr * 64 + fr, fq * 8), boff = lds_byte(wc * 32 + fr, fq * 8);
.Ltr_o_reenter:
	s_barrier
	s_cmpk_gt_i32 s19, 0x407
	v_readfirstlane_b32 s20, v14
	s_cbranch_scc1 .LBB0_2759
	v_lshlrev_b32_e32 v0, 4, v14
	v_add_u32_e32 v1, 0x2000, v0
	v_ashrrev_i32_e32 v2, 31, v1
	v_lshrrev_b32_e32 v2, 22, v2
	v_add_u32_e32 v2, v1, v2
	v_ashrrev_i32_e32 v8, 10, v2
	v_mul_i32_i24_e32 v3, 0x400, v8
	v_sub_u32_e32 v1, v1, v3
	v_lshrrev_b32_e32 v3, 4, v1
	v_bitop3_b32 v1, v3, v1, 32 bitop3:0x6c
	v_ashrrev_i32_e32 v3, 31, v1
	v_lshrrev_b32_e32 v3, 26, v3
	v_add_u32_e32 v3, v1, v3
	v_ashrrev_i32_e32 v9, 6, v3
	v_and_b32_e32 v3, 0xc0, v3
	v_sub_u32_e32 v1, v1, v3
	v_lshlrev_b32_e32 v2, 5, v8
	v_ashrrev_i16_sdwa v1, v182, sext(v1) dst_sel:DWORD dst_unused:UNUSED_PAD src0_sel:DWORD src1_sel:BYTE_0
	v_and_b32_e32 v2, 32, v2
	v_bfe_i32 v10, v1, 0, 16
	s_ashr_i32 s22, s19, 31
	v_add_u32_e32 v1, v2, v10
	v_lshlrev_b32_e32 v2, 3, v8
	s_lshr_b32 s0, s22, 29
	v_and_b32_e32 v2, 0x1ffff0, v2
	s_add_i32 s0, s19, s0
	s_ashr_i32 s1, s20, 6
	v_add_lshl_u32 v2, v9, v2, 11
	s_ashr_i32 s3, s0, 3
	s_and_b32 s0, s0, -8
	s_ashr_i32 s2, s20, 8
	s_lshl_b32 s21, s1, 10
	v_lshl_add_u32 v18, v1, 1, v2
	v_bfe_i32 v2, v14, 27, 1
	s_sub_i32 s0, s19, s0
	v_lshrrev_b32_e32 v2, 22, v2
	s_cmp_lt_i32 s0, 0
	s_movk_i32 s4, 0x82
	v_add_u32_e32 v2, v0, v2
	s_cselect_b32 s4, s4, 0x81
	v_and_b32_e32 v2, 0xfffffc00, v2
	s_mul_i32 s0, s4, s0
	v_sub_u32_e32 v0, v0, v2
	s_add_i32 s0, s0, s3
	v_lshrrev_b32_e32 v2, 4, v0
	s_ashr_i32 s3, s0, 31
	v_bitop3_b32 v2, v2, v0, 32 bitop3:0x6c
	v_ashrrev_i32_e32 v0, 31, v0
	s_lshr_b32 s3, s3, 27
	v_lshrrev_b32_e32 v0, 26, v0
	s_add_i32 s3, s0, s3
	v_ashrrev_i32_e32 v1, 31, v14
	v_add_u32_e32 v0, v2, v0
	s_ashr_i32 s4, s3, 5
	v_lshrrev_b32_e32 v1, 26, v1
	v_ashrrev_i32_e32 v12, 6, v0
	s_lshl_b32 s6, s4, 3
	v_add_u32_e32 v1, v14, v1
	v_mul_i32_i24_e32 v0, 64, v12
	s_sub_i32 s4, 0x102, s6
	v_ashrrev_i32_e32 v11, 6, v1
	v_sub_u32_e32 v0, v2, v0
	s_min_u32 s7, s4, 8
	s_andn2_b32 s3, s3, 31
	v_lshlrev_b32_e32 v1, 5, v11
	v_ashrrev_i16_sdwa v0, v182, sext(v0) dst_sel:DWORD dst_unused:UNUSED_PAD src0_sel:DWORD src1_sel:BYTE_0
	s_sub_i32 s3, s0, s3
	v_cvt_f32_ubyte0_e32 v3, s7
	v_and_b32_e32 v1, 32, v1
	v_bfe_i32 v13, v0, 0, 16
	v_cvt_f32_i32_e32 v2, s3
	v_rcp_iflag_f32_e32 v4, v3
	v_add_u32_e32 v0, v1, v13
	v_lshlrev_b32_e32 v1, 3, v11
	v_and_b32_e32 v1, 0x1ffff0, v1
	v_add_lshl_u32 v1, v12, v1, 11
	v_lshl_add_u32 v134, v0, 1, v1
	v_mul_f32_e32 v0, v2, v4
	v_trunc_f32_e32 v0, v0
	v_fma_f32 v1, -v0, v3, v2
	v_cvt_i32_f32_e32 v0, v0
	s_ashr_i32 s0, s3, 30
	s_or_b32 s0, s0, 1
	v_cmp_ge_f32_e64 s[4:5], |v1|, v3
	s_and_b64 s[4:5], s[4:5], exec
	s_cselect_b32 s0, s0, 0
	v_readfirstlane_b32 s4, v0
	s_add_i32 s0, s4, s0
	s_mul_i32 s4, s0, s7
	s_sub_i32 s3, s3, s4
	s_sext_i32_i8 s3, s3
	s_add_i32 s10, s6, s3
	s_cmpk_lt_u32 s19, 0x400
	s_cbranch_scc0 .Ltr_o_left
	s_lshr_b32 s0, s19, 3
	s_lshr_b32 s3, s0, 5
	s_sub_u32 s3, 3, s3
	s_lshl_b32 s3, s3, 3
	s_and_b32 s10, s19, 7
	s_add_u32 s10, s10, s3
	s_lshl_b32 s10, s10, 3
	s_and_b32 s3, s0, 7
	s_or_b32 s10, s10, s3
	s_bfe_u32 s0, s0, 0x20003
	s_branch .Ltr_o_join

;     DI bool next(int i, Unit& u) const {
;         const long L = (long)i * G + c; if (L >= nwg) return false;
;         int wgid = (int)L; { const int q = nwg / NXCD, r = nwg % NXCD, xcd = wgid % NXCD, off = wgid / NXCD; wgid = (xcd < r ? xcd * (q + 1) : r * (q + 1) + (xcd - r) * q) + off; }
;         const int nig = WGM * nN, gid = wgid / nig, fm = gid * WGM, gsz = (nM - fm) < WGM ? (nM - fm) : WGM;
;         u.pm = fm + ((wgid % nig) % gsz); u.pn = (wgid % nig) / gsz; return true;
;     }
.LBB0_2751:
	s_add_i32 s30, s30, 1
	s_mul_i32 s0, s30, s29
	s_mul_hi_u32 s1, s30, s18
	s_add_i32 s1, s1, s0
	s_mul_i32 s0, s30, s18
	s_add_u32 s6, s0, s19
	s_addc_u32 s7, s1, s22
	v_cmp_gt_i64_e64 s[0:1], s[6:7], v[158:159]
	s_and_b64 vcc, exec, s[0:1]
	s_cbranch_vccnz .LBB0_2753
	s_lshr_b32 s2, s6, 3
	s_lshr_b32 s3, s2, 5
	s_sub_u32 s3, 3, s3
	s_lshl_b32 s3, s3, 3
	s_and_b32 s4, s6, 7
	s_add_u32 s4, s4, s3
	s_lshl_b32 s4, s4, 3
	s_and_b32 s3, s2, 7
	s_or_b32 s4, s4, s3
	s_bfe_u32 s2, s2, 0x20003

; DI int otid() { int t = threadIdx.x; asm volatile("" : "+v"(t)); return t; }
; DI float wave_sum(float x) { x = row_sum16(x); F2 a = swap16(x); x = a.lo + a.hi; F2 b = swap32(x); return b.lo + b.hi; }
; DI void ln_row_wave(const float* src, const float* g, const float* b, float* d32, bf16_t* db, int lane) {
;   float4 v[4]; float s = 0.f;
; #pragma unroll
;   for (int i = 0; i < 4; ++i) { v[i] = reinterpret_cast<const float4*>(src)[lane + 64 * i]; s += v[i].x + v[i].y + v[i].z + v[i].w; }
;   s = wave_sum(s);
;   const float mu = s * (1.f / 1024.f);
;   float q = 0.f;
; #pragma unroll
;   for (int i = 0; i < 4; ++i) { float a = v[i].x - mu, bb = v[i].y - mu, c = v[i].z - mu, d = v[i].w - mu; q += a * a + bb * bb + c * c + d * d; }
;   q = wave_sum(q);
;   const float rstd = rsqrtf(q * (1.f / 1024.f) + LN_EPS);
; DI void phase_ln(const Params& p, int layer, char* smem) {
;   const int tid = otid(), lane = tid & 63;
;   {
;     const int stride = gridDim.x * NWAVES;
;     const float* g = p.ln_g + layer * 1024; const float* b = p.ln_b + layer * 1024;
;     for (int row = blockIdx.x * NWAVES + (tid >> 6); row < MT; row += 2 * stride) {
;       const int row2 = row + stride;
;       if (row2 < MT) ln_rows2(p.out + (size_t)row * 1024, p.out + (size_t)row2 * 1024, g, b, p.out + (size_t)row * 1024, (reinterpret_cast<bf16_t*>(p.ws + OFF_XB)) + (size_t)row * 1024, p.out + (size_t)row2 * 1024, (reinterpret_cast<bf16_t*>(p.ws + OFF_XB)) + (size_t)row2 * 1024, lane);
;       else ln_row_wave(p.out + (size_t)row * 1024, g, b, p.out + (size_t)row * 1024, (reinterpret_cast<bf16_t*>(p.ws + OFF_XB)) + (size_t)row * 1024, lane);
.LBB0_2765:
	s_or_b64 exec, exec, s[0:1]
	v_mov_b32_e32 v1, v153
	s_barrier
	v_readlane_b32 s0, v249, 9
	v_ashrrev_i32_e32 v0, 6, v1
	s_nop 0
	v_add_u32_e32 v0, s0, v0
	s_mov_b32 s0, 0x10200
	v_cmp_gt_i32_e32 vcc, s0, v0
	s_and_saveexec_b64 s[0:1], vcc
	v_readlane_b32 s8, v251, 5
	s_mov_b32 s9, 0x101ff
	s_cbranch_execz .LBB0_2772
	v_readlane_b32 s2, v251, 6
	v_readlane_b32 s3, v251, 7
	s_mov_b32 s5, s3
	v_readlane_b32 s2, v251, 8
	v_readlane_b32 s3, v251, 9
	s_mov_b32 s3, s5
	s_lshl_b32 s4, s2, 10
	v_writelane_b32 v251, s2, 6
	v_readlane_b32 s36, v249, 26
	v_readlane_b32 s50, v249, 40
	v_writelane_b32 v251, s3, 7
	s_lshl_b64 s[2:3], s[4:5], 2
	v_readlane_b32 s51, v249, 41
	s_add_u32 s4, s50, s2
	v_readlane_b32 s48, v249, 38
	s_addc_u32 s5, s51, s3
	v_readlane_b32 s49, v249, 39
	s_add_u32 s2, s48, s2
	v_and_b32_e32 v4, 63, v1
	s_addc_u32 s3, s49, s3
	v_lshlrev_b32_e32 v16, 4, v4
	v_or_b32_e32 v1, 0xc0, v4
	v_lshl_add_u64 v[6:7], s[2:3], 0, v[16:17]
	v_lshl_add_u64 v[8:9], s[4:5], 0, v[16:17]
	v_readlane_b32 s2, v249, 0
	v_readlane_b32 s4, v249, 2
	v_lshlrev_b32_e32 v10, 2, v4
	v_lshlrev_b32_e32 v2, 2, v1
	v_lshlrev_b32_e32 v18, 3, v1
	v_mov_b32_e32 v19, v17
	v_readlane_b32 s3, v249, 1
	v_readlane_b32 s6, v249, 4
	v_readlane_b32 s7, v249, 5
	v_or_b32_e32 v12, 0x100, v10
	v_or_b32_e32 v14, 0x200, v10
	v_lshl_add_u64 v[18:19], s[2:3], 0, v[18:19]
	v_lshl_add_u64 v[22:23], s[6:7], 0, v[16:17]
	s_mov_b64 s[2:3], 0
	v_lshlrev_b32_e32 v24, 1, v2
	v_readlane_b32 s37, v249, 27
	v_readlane_b32 s38, v249, 28
	v_readlane_b32 s39, v249, 29
	v_readlane_b32 s40, v249, 30
	v_readlane_b32 s41, v249, 31
	v_readlane_b32 s42, v249, 32
	v_readlane_b32 s43, v249, 33
	v_readlane_b32 s44, v249, 34
	v_readlane_b32 s45, v249, 35
	v_readlane_b32 s46, v249, 36
	v_readlane_b32 s47, v249, 37
	v_readlane_b32 s5, v249, 3
	v_readlane_b32 s56, v249, 0
	v_readlane_b32 s57, v249, 1
	s_add_u32 s56, s56, 0x2b234000
	s_addc_u32 s57, s57, 0
	v_readlane_b32 s58, v251, 5
	s_lshl_b32 s58, s58, 3
	s_sub_u32 s58, s56, s58
	s_subb_u32 s59, s57, 0
	v_readlane_b32 s60, v251, 8
	s_cmp_eq_u32 s60, 3
	s_cselect_b64 s[60:61], -1, 0
	s_not_b64 s[64:65], s[60:61]
	s_branch .LBB0_2768
.LBB0_2767:
	s_or_b64 exec, exec, s[4:5]
	v_readlane_b32 s8, v251, 5
	v_cvt_pk_bf16_f32 v30, v0, v1
	s_mov_b32 s9, 0x101ff
	v_add_u32_e32 v0, s8, v26
	v_cmp_lt_i32_e32 vcc, s9, v0
	v_lshl_add_u64 v[28:29], v[40:41], 1, v[18:19]
	v_cvt_pk_bf16_f32 v31, v2, v3
	s_or_b64 s[2:3], vcc, s[2:3]
	s_and_saveexec_b64 s[62:63], s[64:65]
	global_store_dwordx2 v[28:29], v[30:31], off
	s_mov_b64 exec, s[62:63]
	s_andn2_b64 exec, exec, s[2:3]
	s_cbranch_execz .LBB0_2772
.LBB0_2768:
	v_readlane_b32 s4, v249, 2
	v_readlane_b32 s5, v249, 3
	v_ashrrev_i32_e32 v1, 31, v0
	v_readlane_b32 s4, v249, 0
	v_add_u32_e32 v26, s8, v0
	v_lshlrev_b64 v[40:41], 10, v[0:1]
	v_lshlrev_b64 v[0:1], 12, v[0:1]
	v_readlane_b32 s6, v249, 4
	v_readlane_b32 s7, v249, 5
	v_readlane_b32 s5, v249, 1
	v_cmp_lt_i32_e32 vcc, s9, v26
	v_lshl_add_u64 v[36:37], s[6:7], 0, v[0:1]
	v_lshl_add_u64 v[28:29], v[40:41], 1, s[4:5]
	v_lshlrev_b32_e32 v16, 4, v4
	v_lshlrev_b32_e32 v34, 1, v10
	v_lshlrev_b32_e32 v32, 1, v12
	v_lshlrev_b32_e32 v30, 1, v14
	s_and_saveexec_b64 s[4:5], vcc
	s_xor_b64 s[4:5], exec, s[4:5]
	s_cbranch_execz .LBB0_2770
	v_lshl_add_u64 v[58:59], v[36:37], 0, v[16:17]
	global_load_dwordx4 v[0:3], v[58:59], off offset:3072
	global_load_dwordx4 v[36:39], v[58:59], off
	global_load_dwordx4 v[42:45], v[58:59], off offset:1024
	global_load_dwordx4 v[46:49], v[58:59], off offset:2048
	global_load_dwordx4 v[50:53], v[6:7], off
	global_load_dwordx4 v[54:57], v[8:9], off
	s_mov_b32 s6, 0x800000
	v_mov_b32_e32 v35, v17
	v_lshl_add_u64 v[34:35], v[28:29], 0, v[34:35]
	v_mov_b32_e32 v33, v17
	v_lshl_add_u64 v[32:33], v[28:29], 0, v[32:33]
	v_mov_b32_e32 v31, v17
	v_lshl_add_u64 v[28:29], v[28:29], 0, v[30:31]
	s_waitcnt vmcnt(5)
	v_add_f32_e32 v5, v0, v1
	s_waitcnt vmcnt(4)
	v_add_f32_e32 v11, v36, v37
	s_waitcnt vmcnt(3)
	v_add_f32_e32 v13, v42, v43
	v_add_f32_e32 v11, v11, v38
	s_waitcnt vmcnt(2)
	v_add_f32_e32 v15, v46, v47
	v_add_f32_e32 v13, v13, v44
	v_add_f32_e32 v11, v11, v39
	v_add_f32_e32 v15, v15, v48
	v_add_f32_e32 v13, v13, v45
	v_add_f32_e32 v11, 0, v11
	v_add_f32_e32 v5, v5, v2
	v_add_f32_e32 v15, v15, v49
	v_add_f32_e32 v11, v11, v13
	v_add_f32_e32 v5, v5, v3
	v_add_f32_e32 v11, v11, v15
	v_add_f32_e32 v5, v11, v5
	s_nop 1
	v_add_f32_dpp v5, v5, v5 quad_perm:[1,0,3,2] row_mask:0xf bank_mask:0xf bound_ctrl:1
	s_nop 1
	v_add_f32_dpp v5, v5, v5 quad_perm:[2,3,0,1] row_mask:0xf bank_mask:0xf bound_ctrl:1
	s_nop 1
	v_add_f32_dpp v5, v5, v5 row_half_mirror row_mask:0xf bank_mask:0xf bound_ctrl:1
	s_nop 1
	v_add_f32_dpp v5, v5, v5 row_mirror row_mask:0xf bank_mask:0xf bound_ctrl:1
	v_mov_b32_e32 v11, v5
	s_nop 1
	v_permlane16_swap_b32_e32 v5, v11
	v_add_f32_e32 v5, v5, v11
	v_mov_b32_e32 v11, v5
	s_nop 1
	v_permlane32_swap_b32_e32 v5, v11
	v_add_f32_e32 v5, v5, v11
	v_mul_f32_e32 v16, 0x3a800000, v5
	v_mov_b32_e32 v100, v16
	v_pk_add_f32 v[36:37], v[36:37], v[16:17] op_sel_hi:[1,0] neg_lo:[0,1] neg_hi:[0,1]
	v_pk_add_f32 v[42:43], v[42:43], v[16:17] op_sel_hi:[1,0] neg_lo:[0,1] neg_hi:[0,1]
	v_pk_add_f32 v[38:39], v[38:39], v[16:17] op_sel_hi:[1,0] neg_lo:[0,1] neg_hi:[0,1]
	v_pk_add_f32 v[44:45], v[44:45], v[16:17] op_sel_hi:[1,0] neg_lo:[0,1] neg_hi:[0,1]
	v_pk_add_f32 v[46:47], v[46:47], v[16:17] op_sel_hi:[1,0] neg_lo:[0,1] neg_hi:[0,1]
	v_pk_add_f32 v[60:61], v[0:1], v[16:17] op_sel_hi:[1,0] neg_lo:[0,1] neg_hi:[0,1]
	v_pk_mul_f32 v[0:1], v[36:37], v[36:37]
	v_pk_mul_f32 v[64:65], v[42:43], v[42:43]
	v_pk_add_f32 v[48:49], v[48:49], v[16:17] op_sel_hi:[1,0] neg_lo:[0,1] neg_hi:[0,1]
; DI bf16x4 pack4(float a, float b, float c, float d) { u32x2v u; u.x = pk2(a, b); u.y = pk2(c, d); return __builtin_bit_cast(bf16x4, u); }
; DI float wave_sum(float x) { x = row_sum16(x); F2 a = swap16(x); x = a.lo + a.hi; F2 b = swap32(x); return b.lo + b.hi; }
; DI void ln_row_wave(const float* src, const float* g, const float* b, float* d32, bf16_t* db, int lane) {
;     ...
;   for (int i = 0; i < 4; ++i) { float a = v[i].x - mu, bb = v[i].y - mu, c = v[i].z - mu, d = v[i].w - mu; q += a * a + bb * bb + c * c + d * d; }
;   q = wave_sum(q);
;   const float rstd = rsqrtf(q * (1.f / 1024.f) + LN_EPS);
; #pragma unroll
;   for (int i = 0; i < 4; ++i) {
;     float4 gg = reinterpret_cast<const float4*>(g)[lane + 64 * i], bb = reinterpret_cast<const float4*>(b)[lane + 64 * i];
;     float4 o;
;     o.x = (v[i].x - mu) * rstd * gg.x + bb.x; o.y = (v[i].y - mu) * rstd * gg.y + bb.y;
;     o.z = (v[i].z - mu) * rstd * gg.z + bb.z; o.w = (v[i].w - mu) * rstd * gg.w + bb.w;
;     reinterpret_cast<float4*>(d32)[lane + 64 * i] = o;
;     st4(db + 4 * (lane + 64 * i), pack4(o.x, o.y, o.z, o.w));
;   }
; DI void ln_rows2(const float* s0, const float* s1, const float* g, const float* b, float* d0, bf16_t* db0, float* d1, bf16_t* db1, int lane) {
;   float4 v0[4], v1[4]; float a0 = 0.f, a1 = 0.f;
; #pragma unroll
;   for (int i = 0; i < 4; ++i) { v0[i] = reinterpret_cast<const float4*>(s0)[lane + 64 * i]; v1[i] = reinterpret_cast<const float4*>(s1)[lane + 64 * i]; }
; #pragma unroll
;   for (int i = 0; i < 4; ++i) { a0 += v0[i].x + v0[i].y + v0[i].z + v0[i].w; a1 += v1[i].x + v1[i].y + v1[i].z + v1[i].w; }
;   a0 = wave_sum(a0); a1 = wave_sum(a1);
	v_pk_add_f32 v[62:63], v[2:3], v[16:17] op_sel_hi:[1,0] neg_lo:[0,1] neg_hi:[0,1]
	v_pk_mul_f32 v[2:3], v[38:39], v[38:39]
	v_pk_mul_f32 v[66:67], v[44:45], v[44:45]
	v_pk_mul_f32 v[68:69], v[46:47], v[46:47]
	v_add_f32_e32 v5, v64, v65
	v_add_f32_e32 v0, v0, v1
	v_pk_mul_f32 v[70:71], v[48:49], v[48:49]
	v_pk_mul_f32 v[72:73], v[60:61], v[60:61]
	v_add_f32_e32 v1, v68, v69
	v_add_f32_e32 v5, v66, v5
	v_add_f32_e32 v0, v2, v0
	v_pk_mul_f32 v[74:75], v[62:63], v[62:63]
	v_add_f32_e32 v11, v72, v73
	v_add_f32_e32 v1, v70, v1
	v_add_f32_e32 v5, v67, v5
	v_add_f32_e32 v0, v3, v0
	v_add_f32_e32 v2, v74, v11
	v_add_f32_e32 v1, v71, v1
	v_add_f32_e32 v0, v0, v5
	v_add_f32_e32 v2, v75, v2
	v_add_f32_e32 v0, v1, v0
	v_add_f32_e32 v0, v2, v0
	s_nop 1
	v_add_f32_dpp v0, v0, v0 quad_perm:[1,0,3,2] row_mask:0xf bank_mask:0xf bound_ctrl:1
	s_nop 1
	v_add_f32_dpp v0, v0, v0 quad_perm:[2,3,0,1] row_mask:0xf bank_mask:0xf bound_ctrl:1
	s_nop 1
	v_add_f32_dpp v0, v0, v0 row_half_mirror row_mask:0xf bank_mask:0xf bound_ctrl:1
	s_nop 1
	v_add_f32_dpp v0, v0, v0 row_mirror row_mask:0xf bank_mask:0xf bound_ctrl:1
	v_mov_b32_e32 v1, v0
	s_nop 1
	v_permlane16_swap_b32_e32 v0, v1
	v_add_f32_e32 v0, v0, v1
	v_mov_b32_e32 v1, v0
	s_nop 1
	v_permlane32_swap_b32_e32 v0, v1
	v_add_f32_e32 v0, v0, v1
	v_fmamk_f32 v0, v0, 0x3a800000, v152
	v_mul_f32_e32 v1, 0x4b800000, v0
	v_cmp_gt_f32_e32 vcc, s6, v0
	s_nop 1
	v_cndmask_b32_e32 v0, v0, v1, vcc
	v_rsq_f32_e32 v0, v0
	s_nop 0
	v_mul_f32_e32 v1, 0x45800000, v0
	v_cndmask_b32_e32 v16, v0, v1, vcc
	v_pk_mul_f32 v[0:1], v[36:37], v[16:17] op_sel_hi:[1,0]
	v_pk_mul_f32 v[2:3], v[38:39], v[16:17] op_sel_hi:[1,0]
	s_waitcnt vmcnt(0)
	v_pk_fma_f32 v[0:1], v[50:51], v[0:1], v[54:55]
	v_pk_fma_f32 v[2:3], v[52:53], v[2:3], v[56:57]
	s_and_saveexec_b64 s[62:63], s[60:61]
	global_store_dwordx4 v[58:59], v[0:3], off
	s_mov_b64 exec, s[62:63]
	v_pk_mul_f32 v[38:39], v[42:43], v[16:17] op_sel_hi:[1,0]
	v_pk_mul_f32 v[42:43], v[44:45], v[16:17] op_sel_hi:[1,0]
	v_cvt_pk_bf16_f32 v0, v0, v1
	v_cvt_pk_bf16_f32 v1, v2, v3
	s_and_saveexec_b64 s[62:63], s[64:65]
	global_store_dwordx2 v[34:35], v[0:1], off
	s_mov_b64 exec, s[62:63]
	global_load_dwordx4 v[0:3], v[6:7], off offset:1024
	s_nop 0
	global_load_dwordx4 v[34:37], v[8:9], off offset:1024
	v_pk_mul_f32 v[30:31], v[46:47], v[16:17] op_sel_hi:[1,0]
	s_waitcnt vmcnt(0)
	v_pk_fma_f32 v[0:1], v[38:39], v[0:1], v[34:35]
	v_pk_fma_f32 v[2:3], v[42:43], v[2:3], v[36:37]
	s_and_saveexec_b64 s[62:63], s[60:61]
	global_store_dwordx4 v[58:59], v[0:3], off offset:1024
	s_mov_b64 exec, s[62:63]
	v_pk_mul_f32 v[36:37], v[48:49], v[16:17] op_sel_hi:[1,0]
	s_nop 0
	v_cvt_pk_bf16_f32 v0, v0, v1
	v_cvt_pk_bf16_f32 v1, v2, v3
	s_and_saveexec_b64 s[62:63], s[64:65]
	global_store_dwordx2 v[32:33], v[0:1], off
	s_mov_b64 exec, s[62:63]
	global_load_dwordx4 v[0:3], v[6:7], off offset:2048
	s_nop 0
	global_load_dwordx4 v[32:35], v[8:9], off offset:2048
	s_waitcnt vmcnt(0)
	v_pk_fma_f32 v[0:1], v[30:31], v[0:1], v[32:33]
	v_pk_fma_f32 v[2:3], v[36:37], v[2:3], v[34:35]
	s_and_saveexec_b64 s[62:63], s[60:61]
	global_store_dwordx4 v[58:59], v[0:3], off offset:2048
	s_mov_b64 exec, s[62:63]
	v_pk_mul_f32 v[32:33], v[60:61], v[16:17] op_sel_hi:[1,0]
	v_pk_mul_f32 v[34:35], v[62:63], v[16:17] op_sel_hi:[1,0]
	v_cvt_pk_bf16_f32 v0, v0, v1
	v_cvt_pk_bf16_f32 v1, v2, v3
	s_and_saveexec_b64 s[62:63], s[64:65]
	global_store_dwordx2 v[28:29], v[0:1], off
	s_mov_b64 exec, s[62:63]
	global_load_dwordx4 v[0:3], v[6:7], off offset:3072
	s_nop 0
	global_load_dwordx4 v[28:31], v[8:9], off offset:3072
	s_waitcnt vmcnt(0)
	v_pk_fma_f32 v[0:1], v[32:33], v[0:1], v[28:29]
	v_pk_fma_f32 v[2:3], v[34:35], v[2:3], v[30:31]
	s_and_saveexec_b64 s[62:63], s[60:61]
	global_store_dwordx4 v[58:59], v[0:3], off offset:3072
	s_mov_b64 exec, s[62:63]
	v_mov_b32_e32 v101, v16
	v_lshlrev_b32_e32 v104, 3, v26
	global_store_dwordx2 v104, v[100:101], s[58:59]
.LBB0_2770:
	s_andn2_saveexec_b64 s[4:5], s[4:5]
	s_cbranch_execz .LBB0_2767
	v_lshl_add_u64 v[36:37], v[36:37], 0, v[16:17]
	global_load_dwordx4 v[40:43], v[36:37], off
	global_load_dwordx4 v[44:47], v[36:37], off offset:1024
	global_load_dwordx4 v[48:51], v[36:37], off offset:2048
	global_load_dwordx4 v[52:55], v[36:37], off offset:3072
	v_ashrrev_i32_e32 v27, 31, v26
	v_lshlrev_b64 v[0:1], 12, v[26:27]
	v_lshl_add_u64 v[38:39], v[22:23], 0, v[0:1]
	global_load_dwordx4 v[56:59], v[38:39], off offset:3072
	global_load_dwordx4 v[60:63], v[38:39], off
	global_load_dwordx4 v[64:67], v[38:39], off offset:1024
	global_load_dwordx4 v[68:71], v[38:39], off offset:2048
	global_load_dwordx4 v[72:75], v[6:7], off
	global_load_dwordx4 v[76:79], v[8:9], off
	v_readlane_b32 s6, v249, 0
	v_lshlrev_b64 v[0:1], 11, v[26:27]
	v_readlane_b32 s7, v249, 1
	v_mov_b32_e32 v35, v17
	v_mov_b32_e32 v33, v17
	v_lshl_add_u64 v[0:1], s[6:7], 0, v[0:1]
	s_mov_b32 s6, 0x3a800000
	v_mov_b32_e32 v31, v17
	v_mov_b32_e32 v25, v17
	s_waitcnt vmcnt(9)
	v_add_f32_e32 v2, v40, v41
	s_waitcnt vmcnt(8)
	v_add_f32_e32 v3, v44, v45
	v_add_f32_e32 v2, v2, v42
	s_waitcnt vmcnt(7)
	v_add_f32_e32 v5, v48, v49
	v_add_f32_e32 v3, v3, v46
	v_add_f32_e32 v2, v2, v43
	s_waitcnt vmcnt(4)
	v_add_f32_e32 v15, v60, v61
	v_add_f32_e32 v11, v52, v53
	v_add_f32_e32 v5, v5, v50
	v_add_f32_e32 v3, v3, v47
	s_waitcnt vmcnt(3)
	v_add_f32_e32 v16, v64, v65
	v_add_f32_e32 v2, 0, v2
	v_add_f32_e32 v15, v15, v62
	v_add_f32_e32 v11, v11, v54
	v_add_f32_e32 v5, v5, v51
	s_waitcnt vmcnt(2)
; DI float wave_sum(float x) { x = row_sum16(x); F2 a = swap16(x); x = a.lo + a.hi; F2 b = swap32(x); return b.lo + b.hi; }
; DI void ln_rows2(const float* s0, const float* s1, const float* g, const float* b, float* d0, bf16_t* db0, float* d1, bf16_t* db1, int lane) {
;     ...
;   for (int i = 0; i < 4; ++i) { a0 += v0[i].x + v0[i].y + v0[i].z + v0[i].w; a1 += v1[i].x + v1[i].y + v1[i].z + v1[i].w; }
;   a0 = wave_sum(a0); a1 = wave_sum(a1);
;   const float mu0 = a0 * (1.f / 1024.f), mu1 = a1 * (1.f / 1024.f);
;   float q0 = 0.f, q1 = 0.f;
; #pragma unroll
;   for (int i = 0; i < 4; ++i) {
;     { float a = v0[i].x - mu0, bb = v0[i].y - mu0, c = v0[i].z - mu0, d = v0[i].w - mu0; q0 += a * a + bb * bb + c * c + d * d; }
;     { float a = v1[i].x - mu1, bb = v1[i].y - mu1, c = v1[i].z - mu1, d = v1[i].w - mu1; q1 += a * a + bb * bb + c * c + d * d; }
;   }
;   q0 = wave_sum(q0); q1 = wave_sum(q1);
;   const float r0 = rsqrtf(q0 * (1.f / 1024.f) + LN_EPS), r1 = rsqrtf(q1 * (1.f / 1024.f) + LN_EPS);
; #pragma unroll
;   for (int i = 0; i < 4; ++i) {
;     const float4 gg = reinterpret_cast<const float4*>(g)[lane + 64 * i], bb = reinterpret_cast<const float4*>(b)[lane + 64 * i];
	v_add_f32_e32 v21, v68, v69
	v_add_f32_e32 v16, v16, v66
	v_add_f32_e32 v2, v2, v3
	v_add_f32_e32 v3, v15, v63
	v_add_f32_e32 v13, v56, v57
	v_add_f32_e32 v11, v11, v55
	v_add_f32_e32 v21, v21, v70
	v_add_f32_e32 v15, v16, v67
	v_add_f32_e32 v2, v2, v5
	v_add_f32_e32 v3, 0, v3
	v_add_f32_e32 v13, v13, v58
	v_add_f32_e32 v16, v21, v71
	v_add_f32_e32 v2, v2, v11
	v_add_f32_e32 v3, v3, v15
	v_add_f32_e32 v13, v13, v59
	v_add_f32_dpp v2, v2, v2 quad_perm:[1,0,3,2] row_mask:0xf bank_mask:0xf bound_ctrl:1
	v_add_f32_e32 v3, v3, v16
	v_add_f32_e32 v3, v3, v13
	v_add_f32_dpp v2, v2, v2 quad_perm:[2,3,0,1] row_mask:0xf bank_mask:0xf bound_ctrl:1
	s_nop 0
	v_add_f32_dpp v3, v3, v3 quad_perm:[1,0,3,2] row_mask:0xf bank_mask:0xf bound_ctrl:1
	v_add_f32_dpp v2, v2, v2 row_half_mirror row_mask:0xf bank_mask:0xf bound_ctrl:1
	s_nop 0
	v_add_f32_dpp v3, v3, v3 quad_perm:[2,3,0,1] row_mask:0xf bank_mask:0xf bound_ctrl:1
	v_add_f32_dpp v2, v2, v2 row_mirror row_mask:0xf bank_mask:0xf bound_ctrl:1
	v_mov_b32_e32 v5, v2
	v_add_f32_dpp v3, v3, v3 row_half_mirror row_mask:0xf bank_mask:0xf bound_ctrl:1
	s_nop 0
	v_permlane16_swap_b32_e32 v2, v5
	v_add_f32_dpp v3, v3, v3 row_mirror row_mask:0xf bank_mask:0xf bound_ctrl:1
	v_add_f32_e32 v2, v2, v5
	v_mov_b32_e32 v5, v3
	v_mov_b32_e32 v11, v2
	s_nop 0
	v_permlane16_swap_b32_e32 v3, v5
	v_permlane32_swap_b32_e32 v2, v11
	v_add_f32_e32 v3, v3, v5
	v_add_f32_e32 v2, v2, v11
	v_mov_b32_e32 v5, v3
	v_mul_f32_e32 v2, 0x3a800000, v2
	v_mov_b32_e32 v100, v2
	s_nop 0
	v_permlane32_swap_b32_e32 v3, v5
	v_pk_add_f32 v[40:41], v[40:41], v[2:3] op_sel_hi:[1,0] neg_lo:[0,1] neg_hi:[0,1]
	v_pk_add_f32 v[80:81], v[44:45], v[2:3] op_sel_hi:[1,0] neg_lo:[0,1] neg_hi:[0,1]
	v_pk_add_f32 v[42:43], v[42:43], v[2:3] op_sel_hi:[1,0] neg_lo:[0,1] neg_hi:[0,1]
	v_pk_add_f32 v[82:83], v[46:47], v[2:3] op_sel_hi:[1,0] neg_lo:[0,1] neg_hi:[0,1]
	v_pk_add_f32 v[48:49], v[48:49], v[2:3] op_sel_hi:[1,0] neg_lo:[0,1] neg_hi:[0,1]
	v_pk_add_f32 v[50:51], v[50:51], v[2:3] op_sel_hi:[1,0] neg_lo:[0,1] neg_hi:[0,1]
	v_pk_add_f32 v[52:53], v[52:53], v[2:3] op_sel_hi:[1,0] neg_lo:[0,1] neg_hi:[0,1]
	v_pk_add_f32 v[54:55], v[54:55], v[2:3] op_sel_hi:[1,0] neg_lo:[0,1] neg_hi:[0,1]
	v_add_f32_e32 v5, v3, v5
	v_pk_mul_f32 v[2:3], v[40:41], v[40:41]
	v_pk_mul_f32 v[46:47], v[80:81], v[80:81]
	v_pk_mul_f32 v[44:45], v[42:43], v[42:43]
	v_pk_mul_f32 v[84:85], v[82:83], v[82:83]
	v_pk_mul_f32 v[86:87], v[48:49], v[48:49]
	v_mul_f32_e32 v16, 0x3a800000, v5
	v_mov_b32_e32 v102, v16
	v_add_f32_e32 v5, v46, v47
	v_add_f32_e32 v2, v2, v3
	v_pk_mul_f32 v[88:89], v[50:51], v[50:51]
	v_pk_mul_f32 v[90:91], v[52:53], v[52:53]
	v_add_f32_e32 v3, v86, v87
	v_add_f32_e32 v5, v84, v5
	v_add_f32_e32 v2, v44, v2
	v_pk_mul_f32 v[92:93], v[54:55], v[54:55]
	v_add_f32_e32 v11, v90, v91
	v_add_f32_e32 v3, v88, v3
	v_add_f32_e32 v5, v85, v5
	v_add_f32_e32 v2, v45, v2
	v_add_f32_e32 v11, v92, v11
	v_add_f32_e32 v3, v89, v3
	v_add_f32_e32 v2, v2, v5
	v_add_f32_e32 v11, v93, v11
	v_add_f32_e32 v2, v3, v2
	v_add_f32_e32 v2, v11, v2
	v_pk_add_f32 v[46:47], v[60:61], v[16:17] op_sel_hi:[1,0] neg_lo:[0,1] neg_hi:[0,1]
	v_pk_add_f32 v[64:65], v[64:65], v[16:17] op_sel_hi:[1,0] neg_lo:[0,1] neg_hi:[0,1]
	v_add_f32_dpp v2, v2, v2 quad_perm:[1,0,3,2] row_mask:0xf bank_mask:0xf bound_ctrl:1
	v_pk_add_f32 v[60:61], v[62:63], v[16:17] op_sel_hi:[1,0] neg_lo:[0,1] neg_hi:[0,1]
	v_pk_mul_f32 v[62:63], v[46:47], v[46:47]
	v_add_f32_dpp v2, v2, v2 quad_perm:[2,3,0,1] row_mask:0xf bank_mask:0xf bound_ctrl:1
	v_pk_add_f32 v[66:67], v[66:67], v[16:17] op_sel_hi:[1,0] neg_lo:[0,1] neg_hi:[0,1]
	v_pk_mul_f32 v[86:87], v[64:65], v[64:65]
	v_add_f32_dpp v2, v2, v2 row_half_mirror row_mask:0xf bank_mask:0xf bound_ctrl:1
	v_pk_mul_f32 v[84:85], v[60:61], v[60:61]
	v_pk_mul_f32 v[88:89], v[66:67], v[66:67]
	v_add_f32_dpp v2, v2, v2 row_mirror row_mask:0xf bank_mask:0xf bound_ctrl:1
	v_mov_b32_e32 v3, v2
	s_nop 1
	v_permlane16_swap_b32_e32 v2, v3
	v_add_f32_e32 v3, v2, v3
	v_add_f32_e32 v2, v86, v87
	v_add_f32_e32 v5, v62, v63
	v_pk_add_f32 v[68:69], v[68:69], v[16:17] op_sel_hi:[1,0] neg_lo:[0,1] neg_hi:[0,1]
	v_add_f32_e32 v2, v88, v2
	v_add_f32_e32 v5, v84, v5
	v_pk_add_f32 v[70:71], v[70:71], v[16:17] op_sel_hi:[1,0] neg_lo:[0,1] neg_hi:[0,1]
	v_pk_mul_f32 v[90:91], v[68:69], v[68:69]
	v_add_f32_e32 v2, v89, v2
	v_add_f32_e32 v5, v85, v5
	v_pk_mul_f32 v[92:93], v[70:71], v[70:71]
	v_add_f32_e32 v2, v5, v2
	v_add_f32_e32 v5, v90, v91
	v_pk_add_f32 v[56:57], v[56:57], v[16:17] op_sel_hi:[1,0] neg_lo:[0,1] neg_hi:[0,1]
	v_add_f32_e32 v5, v92, v5
	v_pk_add_f32 v[58:59], v[58:59], v[16:17] op_sel_hi:[1,0] neg_lo:[0,1] neg_hi:[0,1]
	v_pk_mul_f32 v[94:95], v[56:57], v[56:57]
	v_add_f32_e32 v5, v93, v5
	v_pk_mul_f32 v[96:97], v[58:59], v[58:59]
	v_add_f32_e32 v2, v5, v2
	v_add_f32_e32 v5, v94, v95
	v_add_f32_e32 v5, v96, v5
	v_add_f32_e32 v5, v97, v5
	v_add_f32_e32 v2, v5, v2
	v_mov_b32_e32 v45, v3
	s_nop 1
	v_permlane32_swap_b32_e32 v3, v45
	v_add_f32_dpp v2, v2, v2 quad_perm:[1,0,3,2] row_mask:0xf bank_mask:0xf bound_ctrl:1
	s_nop 1
	v_add_f32_dpp v2, v2, v2 quad_perm:[2,3,0,1] row_mask:0xf bank_mask:0xf bound_ctrl:1
	s_nop 1
	v_add_f32_dpp v2, v2, v2 row_half_mirror row_mask:0xf bank_mask:0xf bound_ctrl:1
	s_nop 1
	v_add_f32_dpp v2, v2, v2 row_mirror row_mask:0xf bank_mask:0xf bound_ctrl:1
	v_mov_b32_e32 v5, v2
	s_nop 1
	v_permlane16_swap_b32_e32 v2, v5
	v_add_f32_e32 v2, v2, v5
	v_mov_b32_e32 v44, v2
	s_nop 1
	v_permlane32_swap_b32_e32 v2, v44
	v_pk_add_f32 v[2:3], v[2:3], v[44:45]
	v_lshl_add_u64 v[44:45], v[28:29], 0, v[34:35]
	v_pk_fma_f32 v[2:3], v[2:3], s[6:7], v[152:153] op_sel_hi:[1,0,0]
	s_mov_b32 s6, 0x800000
	v_mul_f32_e32 v5, 0x4b800000, v3
	v_cmp_gt_f32_e32 vcc, s6, v3
	v_lshl_add_u64 v[34:35], v[0:1], 0, v[34:35]
	s_nop 0
	v_cndmask_b32_e32 v3, v3, v5, vcc
	v_rsq_f32_e32 v3, v3
	s_nop 0
	v_mul_f32_e32 v5, 0x45800000, v3
	v_cndmask_b32_e32 v16, v3, v5, vcc
	v_mul_f32_e32 v3, 0x4b800000, v2
	v_cmp_gt_f32_e32 vcc, s6, v2
	v_pk_mul_f32 v[40:41], v[40:41], v[16:17] op_sel_hi:[1,0]
	v_pk_mul_f32 v[42:43], v[42:43], v[16:17] op_sel_hi:[1,0]
	v_cndmask_b32_e32 v2, v2, v3, vcc
	v_rsq_f32_e32 v5, v2
	s_waitcnt vmcnt(0)
; DI bf16x4 pack4(float a, float b, float c, float d) { u32x2v u; u.x = pk2(a, b); u.y = pk2(c, d); return __builtin_bit_cast(bf16x4, u); }
; DI void ln_rows2(const float* s0, const float* s1, const float* g, const float* b, float* d0, bf16_t* db0, float* d1, bf16_t* db1, int lane) {
;     ...
;   for (int i = 0; i < 4; ++i) {
;     const float4 gg = reinterpret_cast<const float4*>(g)[lane + 64 * i], bb = reinterpret_cast<const float4*>(b)[lane + 64 * i];
;     float4 o;
;     o.x = (v0[i].x - mu0) * r0 * gg.x + bb.x; o.y = (v0[i].y - mu0) * r0 * gg.y + bb.y; o.z = (v0[i].z - mu0) * r0 * gg.z + bb.z; o.w = (v0[i].w - mu0) * r0 * gg.w + bb.w;
;     reinterpret_cast<float4*>(d0)[lane + 64 * i] = o; st4(db0 + 4 * (lane + 64 * i), pack4(o.x, o.y, o.z, o.w));
;     o.x = (v1[i].x - mu1) * r1 * gg.x + bb.x; o.y = (v1[i].y - mu1) * r1 * gg.y + bb.y; o.z = (v1[i].z - mu1) * r1 * gg.z + bb.z; o.w = (v1[i].w - mu1) * r1 * gg.w + bb.w;
;     reinterpret_cast<float4*>(d1)[lane + 64 * i] = o; st4(db1 + 4 * (lane + 64 * i), pack4(o.x, o.y, o.z, o.w));
;   }
; }
	v_pk_fma_f32 v[40:41], v[72:73], v[40:41], v[76:77]
	v_pk_fma_f32 v[42:43], v[74:75], v[42:43], v[78:79]
	v_cvt_pk_bf16_f32 v2, v40, v41
	v_mul_f32_e32 v11, 0x45800000, v5
	v_cndmask_b32_e32 v62, v5, v11, vcc
	v_cvt_pk_bf16_f32 v3, v42, v43
	s_and_saveexec_b64 s[62:63], s[60:61]
	global_store_dwordx4 v[36:37], v[40:43], off
	s_mov_b64 exec, s[62:63]
	v_pk_mul_f32 v[64:65], v[64:65], v[62:63] op_sel_hi:[1,0]
	v_pk_mul_f32 v[66:67], v[66:67], v[62:63] op_sel_hi:[1,0]
	v_pk_mul_f32 v[40:41], v[46:47], v[62:63] op_sel_hi:[1,0]
	v_pk_mul_f32 v[42:43], v[60:61], v[62:63] op_sel_hi:[1,0]
	v_pk_fma_f32 v[40:41], v[72:73], v[40:41], v[76:77]
	v_pk_fma_f32 v[42:43], v[74:75], v[42:43], v[78:79]
	v_cvt_pk_bf16_f32 v46, v40, v41
	v_cvt_pk_bf16_f32 v47, v42, v43
	s_and_saveexec_b64 s[62:63], s[64:65]
	global_store_dwordx2 v[44:45], v[2:3], off
	s_mov_b64 exec, s[62:63]
	s_and_saveexec_b64 s[62:63], s[60:61]
	global_store_dwordx4 v[38:39], v[40:43], off
	s_mov_b64 exec, s[62:63]
	s_and_saveexec_b64 s[62:63], s[64:65]
	global_store_dwordx2 v[34:35], v[46:47], off
	s_mov_b64 exec, s[62:63]
	global_load_dwordx4 v[40:43], v[6:7], off offset:1024
	s_nop 0
	global_load_dwordx4 v[44:47], v[8:9], off offset:1024
	v_lshl_add_u64 v[2:3], v[28:29], 0, v[32:33]
	v_lshl_add_u64 v[60:61], v[0:1], 0, v[32:33]
	v_pk_mul_f32 v[32:33], v[80:81], v[16:17] op_sel_hi:[1,0]
	v_pk_mul_f32 v[34:35], v[82:83], v[16:17] op_sel_hi:[1,0]
	s_waitcnt vmcnt(0)
	v_pk_fma_f32 v[32:33], v[32:33], v[40:41], v[44:45]
	v_pk_fma_f32 v[34:35], v[34:35], v[42:43], v[46:47]
	v_pk_fma_f32 v[40:41], v[64:65], v[40:41], v[44:45]
	v_pk_fma_f32 v[42:43], v[66:67], v[42:43], v[46:47]
	s_and_saveexec_b64 s[62:63], s[60:61]
	global_store_dwordx4 v[36:37], v[32:35], off offset:1024
	s_mov_b64 exec, s[62:63]
	v_lshl_add_u64 v[46:47], v[0:1], 0, v[30:31]
	v_pk_mul_f32 v[0:1], v[48:49], v[16:17] op_sel_hi:[1,0]
	v_cvt_pk_bf16_f32 v32, v32, v33
	v_cvt_pk_bf16_f32 v33, v34, v35
	v_cvt_pk_bf16_f32 v34, v40, v41
	v_cvt_pk_bf16_f32 v35, v42, v43
	s_and_saveexec_b64 s[62:63], s[64:65]
	global_store_dwordx2 v[2:3], v[32:33], off
	s_mov_b64 exec, s[62:63]
	s_and_saveexec_b64 s[62:63], s[60:61]
	global_store_dwordx4 v[38:39], v[40:43], off offset:1024
	s_mov_b64 exec, s[62:63]
	s_and_saveexec_b64 s[62:63], s[64:65]
	global_store_dwordx2 v[60:61], v[34:35], off
	s_mov_b64 exec, s[62:63]
	global_load_dwordx4 v[32:35], v[6:7], off offset:2048
	s_nop 0
	global_load_dwordx4 v[40:43], v[8:9], off offset:2048
	v_pk_mul_f32 v[2:3], v[50:51], v[16:17] op_sel_hi:[1,0]
	v_lshl_add_u64 v[44:45], v[28:29], 0, v[30:31]
	v_pk_mul_f32 v[30:31], v[68:69], v[62:63] op_sel_hi:[1,0]
	v_pk_mul_f32 v[48:49], v[70:71], v[62:63] op_sel_hi:[1,0]
	v_lshl_add_u64 v[28:29], v[28:29], 0, v[24:25]
	s_waitcnt vmcnt(0)
	v_pk_fma_f32 v[0:1], v[0:1], v[32:33], v[40:41]
	v_pk_fma_f32 v[2:3], v[2:3], v[34:35], v[42:43]
	v_pk_fma_f32 v[30:31], v[30:31], v[32:33], v[40:41]
	v_pk_fma_f32 v[32:33], v[48:49], v[34:35], v[42:43]
	s_and_saveexec_b64 s[62:63], s[60:61]
	global_store_dwordx4 v[36:37], v[0:3], off offset:2048
	s_mov_b64 exec, s[62:63]
	v_pk_mul_f32 v[34:35], v[52:53], v[16:17] op_sel_hi:[1,0]
	v_pk_mul_f32 v[48:49], v[58:59], v[62:63] op_sel_hi:[1,0]
	v_cvt_pk_bf16_f32 v0, v0, v1
	v_cvt_pk_bf16_f32 v1, v2, v3
	v_cvt_pk_bf16_f32 v2, v30, v31
	v_cvt_pk_bf16_f32 v3, v32, v33
	s_and_saveexec_b64 s[62:63], s[64:65]
	global_store_dwordx2 v[44:45], v[0:1], off
	s_mov_b64 exec, s[62:63]
	s_and_saveexec_b64 s[62:63], s[60:61]
	global_store_dwordx4 v[38:39], v[30:33], off offset:2048
	s_mov_b64 exec, s[62:63]
	s_and_saveexec_b64 s[62:63], s[64:65]
	global_store_dwordx2 v[46:47], v[2:3], off
	s_mov_b64 exec, s[62:63]
	global_load_dwordx4 v[0:3], v[6:7], off offset:3072
	s_nop 0
	global_load_dwordx4 v[30:33], v[8:9], off offset:3072
	v_pk_mul_f32 v[44:45], v[54:55], v[16:17] op_sel_hi:[1,0]
	v_pk_mul_f32 v[46:47], v[56:57], v[62:63] op_sel_hi:[1,0]
	v_lshlrev_b64 v[40:41], 10, v[26:27]
	s_waitcnt vmcnt(0)
	v_pk_fma_f32 v[42:43], v[34:35], v[0:1], v[30:31]
	v_pk_fma_f32 v[44:45], v[44:45], v[2:3], v[32:33]
	v_pk_fma_f32 v[0:1], v[46:47], v[0:1], v[30:31]
	v_pk_fma_f32 v[2:3], v[48:49], v[2:3], v[32:33]
	v_cvt_pk_bf16_f32 v30, v42, v43
	v_cvt_pk_bf16_f32 v31, v44, v45
	s_and_saveexec_b64 s[62:63], s[60:61]
	global_store_dwordx4 v[36:37], v[42:45], off offset:3072
	s_mov_b64 exec, s[62:63]
	s_and_saveexec_b64 s[62:63], s[64:65]
	global_store_dwordx2 v[28:29], v[30:31], off
	s_mov_b64 exec, s[62:63]
	s_and_saveexec_b64 s[62:63], s[60:61]
	global_store_dwordx4 v[38:39], v[0:3], off offset:3072
	s_mov_b64 exec, s[62:63]
	v_mov_b32_e32 v101, v16
	v_mov_b32_e32 v103, v62
	v_lshlrev_b32_e32 v104, 3, v26
	global_store_dwordx2 v104, v[100:101], s[58:59]
	global_store_dwordx2 v104, v[102:103], s[56:57]
	s_branch .LBB0_2767
